# attention older half: first QK MFMA issued after one fragment stage (S0 fragments read first)
# speedup vs baseline: 1.0011x; 1.0011x over previous
; #define LAS __attribute__((address_space(3)))
; __device__ __forceinline__ void attn_issue_k(const Frame& F, const unsigned char* ktile, LAS unsigned char* buf) {
;     unsigned lo = F.lane * 16; asm volatile("" : "+v"(lo));
; #pragma unroll
;     for (int j = 0; j < 3; ++j) __builtin_amdgcn_global_load_lds((const unsigned*)(ktile + (size_t)(F.wave * 3 + j) * 1024 + lo), (LAS unsigned*)(buf + (F.wave * 3 + j) * 1024), 16, 0, 0);
; }
.LBB0_1027:
	s_setprio 1
	s_cmp_le_u32 s72, s70
	s_cselect_b64 s[0:1], -1, 0
	s_cmp_gt_u32 s72, s70
	s_cbranch_scc1 .Lmy_attn_skipqk_a
	ds_read_b128 v[4:7], v2
	ds_read_b128 v[12:15], v16
	ds_read_b128 v[8:11], v2 offset:12288
	ds_read_b128 v[180:183], v16 offset:12288
	v_add_u32_e32 v17, s88, v176
	v_add_u32_e32 v179, s88, v177
	s_waitcnt lgkmcnt(2)
	v_mfma_f32_32x32x16_bf16 v[98:113], v[4:7], v[114:117], 0
	ds_read_b128 v[184:187], v17
	ds_read_b128 v[188:191], v17 offset:12288
	ds_read_b128 v[192:195], v179
	ds_read_b128 v[196:199], v179 offset:12288
	v_mfma_f32_32x32x16_bf16 v[98:113], v[12:15], v[118:121], v[98:113]
	ds_read_b128 v[200:203], v2 offset:128
	ds_read_b128 v[204:207], v2 offset:12416
	ds_read_b128 v[208:211], v16 offset:128
	ds_read_b128 v[212:215], v16 offset:12416
	s_waitcnt lgkmcnt(8)
	v_mfma_f32_32x32x16_bf16 v[82:97], v[8:11], v[114:117], 0
	s_add_i32 m0, vcc_lo, s56
	s_add_u32 s100, s98, s8
	s_addc_u32 s101, s99, s9
	global_load_lds_dwordx4 v164, s[100:101]
	v_mfma_f32_32x32x16_bf16 v[82:97], v[180:183], v[118:121], v[82:97]
	s_add_i32 m0, vcc_lo, s57
	s_add_u32 s100, s98, s10
	s_addc_u32 s101, s99, s11
	global_load_lds_dwordx4 v164, s[100:101]
	s_add_i32 m0, vcc_lo, s58
	s_add_u32 s100, s98, s12
	s_addc_u32 s101, s99, s13
	global_load_lds_dwordx4 v164, s[100:101]
	ds_read_b128 v[4:7], v17 offset:128
	ds_read_b128 v[8:11], v17 offset:12416
	ds_read_b128 v[12:15], v179 offset:128
	ds_read_b128 v[180:183], v179 offset:12416
	s_waitcnt lgkmcnt(8)
	v_mfma_f32_32x32x16_bf16 v[98:113], v[184:187], v[122:125], v[98:113]
	v_mfma_f32_32x32x16_bf16 v[98:113], v[192:195], v[126:129], v[98:113]
	v_mfma_f32_32x32x16_bf16 v[82:97], v[188:191], v[122:125], v[82:97]
	v_mfma_f32_32x32x16_bf16 v[82:97], v[196:199], v[126:129], v[82:97]
	ds_read_b128 v[184:187], v2 offset:256
	ds_read_b128 v[188:191], v2 offset:12544
	ds_read_b128 v[192:195], v16 offset:256
	ds_read_b128 v[196:199], v16 offset:12544
	s_waitcnt lgkmcnt(8)
	v_mfma_f32_32x32x16_bf16 v[98:113], v[200:203], v[130:133], v[98:113]
	v_mfma_f32_32x32x16_bf16 v[98:113], v[208:211], v[134:137], v[98:113]
	v_mfma_f32_32x32x16_bf16 v[82:97], v[204:207], v[130:133], v[82:97]
	v_mfma_f32_32x32x16_bf16 v[82:97], v[212:215], v[134:137], v[82:97]
	ds_read_b128 v[200:203], v17 offset:256
	ds_read_b128 v[204:207], v17 offset:12544
	ds_read_b128 v[208:211], v179 offset:256
	ds_read_b128 v[212:215], v179 offset:12544
	s_waitcnt lgkmcnt(8)
	v_mfma_f32_32x32x16_bf16 v[98:113], v[4:7], v[138:141], v[98:113]
	v_mfma_f32_32x32x16_bf16 v[98:113], v[12:15], v[142:145], v[98:113]
	v_mfma_f32_32x32x16_bf16 v[82:97], v[8:11], v[138:141], v[82:97]
	v_mfma_f32_32x32x16_bf16 v[82:97], v[180:183], v[142:145], v[82:97]
	s_waitcnt lgkmcnt(4)
	v_mfma_f32_32x32x16_bf16 v[98:113], v[184:187], v[146:149], v[98:113]
	v_mfma_f32_32x32x16_bf16 v[98:113], v[192:195], v[154:157], v[98:113]
	v_mfma_f32_32x32x16_bf16 v[82:97], v[188:191], v[146:149], v[82:97]
	v_mfma_f32_32x32x16_bf16 v[82:97], v[196:199], v[154:157], v[82:97]
	s_waitcnt lgkmcnt(0)
	v_mfma_f32_32x32x16_bf16 v[98:113], v[200:203], v[150:153], v[98:113]
	v_mfma_f32_32x32x16_bf16 v[98:113], v[208:211], v[158:161], v[98:113]
	v_mfma_f32_32x32x16_bf16 v[82:97], v[204:207], v[150:153], v[82:97]
	v_mfma_f32_32x32x16_bf16 v[82:97], v[212:215], v[158:161], v[82:97]
	s_branch .LBB0_1030
